# attention phase: one static s_setprio 1 for waves 4-7 (reset at phase end) to break the lockstep of the two same-program waves per SIMD
# speedup vs baseline: 1.0004x; 1.0004x over previous
; #define LAS __attribute__((address_space(3)))
; #define AREF(r, L_) do { const int h_ = (L_) & 15, qb_ = 31 - ((L_) >> 4);     (r).Q = Qb + ((size_t)h_ * S + (size_t)qb_ * 256) * HD; (r).K = Kb + (size_t)h_ * S * HD; (r).V = Vb + (size_t)h_ * S * HD; \
;                               (r).CB = cb + (size_t)h_ * S; (r).O = OB + (size_t)qb_ * 256 * ALD + h_ * HD; (r).P0 = qb_ * 256; (r).jlo = jtab[h_ * 32 + qb_]; } while (0)
; __global__ void __launch_bounds__(NTHREADS, 2) fwd_megakernel(Args args) {
;     ...
;             for (int rep_ = 0; rep_ < REP_ATT; ++rep_) if constexpr (PH(4)) {
;                 char* alds = (char*)lds_raw;
;                 const bf16_t* Qb = QKV; const bf16_t* Kb = QKV + (size_t)NH * S * HD; const bf16_t* Vb = QKV + (size_t)2 * NH * S * HD;
;                 constexpr int TOTAL = NH * (S / 256); const int W = S;
;                 volatile LAS unsigned* sched = (volatile LAS unsigned*)(lds + LDS_BYTES - 32);
;                 unsigned* ctr = (unsigned*)args.ws + 3584 + 64 * j + 16 * rep_;
;                 int L = vcu;
;                 if (L < TOTAL) {
;     ...
;                     att::BlockRef cur, nxt; AREF(cur, L);
;                     if (threadIdx.x == 0) sched[0] = atomicAdd(ctr, 1u) + (unsigned)G;
.LBB0_477:
	s_or_b64 exec, exec, s[28:29]
	v_readlane_b32 s0, v254, 35
	v_readlane_b32 s1, v254, 36
	s_and_b64 vcc, exec, s[0:1]
	s_waitcnt lgkmcnt(0)
	s_barrier
	s_cbranch_vccz .LBB0_660
	v_readfirstlane_b32 s0, v236
	s_nop 0
	s_cmpk_lt_u32 s0, 0x100
	s_cbranch_scc1 .Lattn_prio_skip
	s_setprio 1
.Lattn_prio_skip:
	v_readlane_b32 s0, v254, 55
	v_readlane_b32 s1, v254, 56
	v_readlane_b32 s6, v254, 33
	s_nop 3
	global_load_dword v0, v139, s[0:1]
	v_readlane_b32 s0, v253, 13
	v_readlane_b32 s1, v253, 14
	s_lshl_b32 s30, s0, 6
	s_lshl_b64 s[0:1], s[30:31], 2
	s_add_u32 s70, s6, s0
	v_readlane_b32 s0, v254, 34
	s_addc_u32 s71, s0, s1
	s_waitcnt vmcnt(0)
	v_readfirstlane_b32 s58, v0
	s_mov_b64 s[28:29], exec
	v_readlane_b32 s0, v252, 11
	v_readlane_b32 s1, v252, 12
	s_and_b64 s[0:1], s[28:29], s[0:1]
	s_mov_b64 exec, s[0:1]
	s_cbranch_execz .LBB0_482
	s_mov_b64 s[40:41], exec
	v_mbcnt_lo_u32_b32 v0, s40, 0
	v_mbcnt_hi_u32_b32 v0, s41, v0
	v_cmp_eq_u32_e32 vcc, 0, v0
	s_and_saveexec_b64 s[38:39], vcc
	s_cbranch_execz .LBB0_481
	s_bcnt1_i32_b64 s0, s[40:41]
	v_mov_b32_e32 v1, s0
	global_atomic_add v1, v139, v1, s[70:71] sc0

; __device__ __forceinline__ void xcd_barrier(const XcdBarrier& b) {
;     asm volatile("s_waitcnt vmcnt(0)" ::: "memory");
;     __syncthreads();
;     if (threadIdx.x == 0) {
;         unsigned* bar = b.bar;
;         __builtin_amdgcn_s_waitcnt(0);
;         unsigned nloc = b.st[0], nx = b.st[1];
;         if (nloc == 0u) { xcd_barrier_complete(bar, b.x, nloc, nx); b.st[0] = nloc; b.st[1] = nx; }
.LBB0_660:
	s_setprio 0
	s_waitcnt vmcnt(0)
	s_barrier
	s_mov_b64 s[0:1], exec
	v_readlane_b32 s6, v252, 11
	v_readlane_b32 s7, v252, 12
	s_and_b64 s[6:7], s[0:1], s[6:7]
	s_xor_b64 s[28:29], s[6:7], s[0:1]
	s_mov_b64 exec, s[6:7]
	s_cbranch_execz .LBB0_713
	v_readlane_b32 s0, v255, 62
	s_waitcnt vmcnt(0) expcnt(0) lgkmcnt(0)
	s_nop 0
	v_mov_b32_e32 v0, s0
	ds_read_b32 v2, v0
	v_readlane_b32 s0, v255, 63
	s_waitcnt lgkmcnt(0)
	v_cmp_ne_u32_e32 vcc, 0, v2
	v_mov_b32_e32 v0, s0
	ds_read_b32 v0, v0
	s_cbranch_vccnz .LBB0_676
	v_readlane_b32 s6, v252, 8
	v_readlane_b32 s7, v252, 9
	s_load_dwordx2 s[0:1], s[6:7], 0x4
	s_waitcnt lgkmcnt(0)
	s_mul_i32 s0, s0, s33
	s_mul_i32 s0, s0, s1
	s_mov_b32 s1, 1
	s_branch .LBB0_664
